# conversion jobs split: about 14 per workgroup in the idle last-round slots of the gate/up GEMM phases, remainder stays in the down GEMM phases
# baseline (speedup 1.0000x reference)
; __device__ void run_phase(const KP& p_, int ph) {
;     ...
;     if (q == 0) { gemm_phase<1, NGU, DM>(p, l, hb, Wl + W_GUA); if (l == 0) { plo = 1408; phi = 2112; pfirst = (132 * 22) % p.nblk; } }
.LBB0_1151:
	v_readlane_b32 s0, v255, 53
	v_readlane_b32 s1, v255, 54
	s_andn2_b64 vcc, exec, s[0:1]
	s_cbranch_vccnz .LBB0_1153
	v_readlane_b32 s0, v255, 43
	s_abs_i32 s0, s0
	v_readlane_b32 s1, v255, 44
	v_cvt_f32_u32_e32 v0, s0
	s_sub_i32 s1, 0, s0
	s_movk_i32 s33, 0xeb0
	s_movk_i32 s95, 0x580
	v_rcp_iflag_f32_e32 v0, v0
	s_nop 0
	v_mul_f32_e32 v0, 0x4f7ffffe, v0
	v_cvt_u32_f32_e32 v0, v0
	s_nop 0
	v_readfirstlane_b32 s2, v0
	s_mul_i32 s1, s1, s2
	s_mul_hi_u32 s1, s2, s1
	s_add_i32 s2, s2, s1
	s_mul_hi_u32 s1, s2, 0xb58
	s_mul_i32 s1, s1, s0
	s_sub_i32 s1, 0xb58, s1
	s_sub_i32 s2, s1, s0
	s_cmp_ge_u32 s1, s0
	s_cselect_b32 s1, s2, s1
	s_sub_i32 s2, s1, s0
	s_cmp_ge_u32 s1, s0
	s_cselect_b32 s67, s2, s1
	s_mov_b64 s[88:89], -1
	s_branch .LBB0_27
.LBB0_1153:
	s_movk_i32 s67, 0x58
	s_movk_i32 s95, 0x1d80
	s_movk_i32 s33, 0x26b0
	s_mov_b64 s[88:89], -1
	s_branch .LBB0_27

; __device__ void run_phase(const KP& p_, int ph) {
;     ...
;     else if (q == 1) { gemm_phase<2, DM, DFF>(p, l, U, Wl + W_DA); if (l == 0) { plo = 2112; phi = 5440; } else { plo = 7552; phi = 10880; } }
.LBB0_1167:
	v_readlane_b32 s0, v255, 53
	v_readlane_b32 s1, v255, 54
	s_and_b64 s[0:1], s[0:1], exec
	s_movk_i32 s0, 0x2a80
	s_cselect_b32 s33, 0x1540, s0
	s_movk_i32 s0, 0xeb0
	s_cselect_b32 s95, s0, 0x26b0
	s_mov_b64 s[0:1], 0
	v_writelane_b32 v255, s0, 62
	s_mov_b64 s[88:89], -1
	s_mov_b32 s67, 16
	v_writelane_b32 v255, s1, 63
	s_mov_b64 s[44:45], 0
	s_branch .LBB0_1125
